# accumulator zeroing at GEMM unit heads: 128 v_mov_b32 -> 64 v_mov_b64 of constant 0
# speedup vs baseline: 1.0064x; 1.0026x over previous
.LBB0_149:
	s_ashr_i32 s79, s78, 31
	s_lshl_b64 s[6:7], s[78:79], 11
	s_add_u32 s82, s34, s6
	s_addc_u32 s83, s35, s7
	s_and_b64 s[6:7], s[0:1], exec
	s_cselect_b32 s8, s83, s3
	s_cselect_b32 s9, s82, s2
	s_ashr_i32 s81, s80, 31
	s_lshl_b64 s[6:7], s[80:81], 11
	s_add_u32 s84, s40, s6
	s_addc_u32 s85, s41, s7
	s_and_b64 s[6:7], s[0:1], exec
	s_cselect_b32 s79, s85, s5
	s_cselect_b32 s81, s84, s4
	s_add_u32 s2, s2, 0x40080
	s_addc_u32 s3, s3, 0
	s_add_u32 s87, s4, 0x100
	v_mov_b32_e32 v0, 0
	s_addc_u32 s88, s5, 0
	s_mov_b32 s89, -2
	v_mov_b32_e32 v1, v0
	v_mov_b32_e32 v2, v0
	v_mov_b32_e32 v3, v0
	v_mov_b32_e32 v4, v0
	v_mov_b32_e32 v5, v0
	v_mov_b32_e32 v6, v0
	v_mov_b32_e32 v7, v0
	v_mov_b32_e32 v16, v0
	v_mov_b32_e32 v17, v0
	v_mov_b32_e32 v18, v0
	v_mov_b32_e32 v19, v0
	v_mov_b32_e32 v20, v0
	v_mov_b32_e32 v21, v0
	v_mov_b32_e32 v22, v0
	v_mov_b32_e32 v23, v0
	v_mov_b32_e32 v32, v0
	v_mov_b32_e32 v33, v0
	v_mov_b32_e32 v34, v0
	v_mov_b32_e32 v35, v0
	s_waitcnt vmcnt(0)
	v_mov_b64_e32 v[8:9], 0
	v_mov_b64_e32 v[10:11], 0
	v_mov_b64_e32 v[12:13], 0
	v_mov_b64_e32 v[14:15], 0
	v_mov_b64_e32 v[24:25], 0
	v_mov_b64_e32 v[26:27], 0
	v_mov_b64_e32 v[28:29], 0
	v_mov_b64_e32 v[30:31], 0
	v_mov_b64_e32 v[36:37], 0
	v_mov_b64_e32 v[38:39], 0
	v_mov_b64_e32 v[40:41], 0
	v_mov_b64_e32 v[42:43], 0
	v_mov_b64_e32 v[44:45], 0
	v_mov_b64_e32 v[46:47], 0
	v_mov_b64_e32 v[64:65], 0
	v_mov_b64_e32 v[66:67], 0
	v_mov_b64_e32 v[68:69], 0
	v_mov_b64_e32 v[70:71], 0
	v_mov_b64_e32 v[72:73], 0
	v_mov_b64_e32 v[74:75], 0
	v_mov_b64_e32 v[76:77], 0
	v_mov_b64_e32 v[78:79], 0
	v_mov_b64_e32 v[80:81], 0
	v_mov_b64_e32 v[82:83], 0
	v_mov_b64_e32 v[84:85], 0
	v_mov_b64_e32 v[86:87], 0
	v_mov_b64_e32 v[88:89], 0
	v_mov_b64_e32 v[90:91], 0
	v_mov_b64_e32 v[92:93], 0
	v_mov_b64_e32 v[94:95], 0
	v_mov_b64_e32 v[96:97], 0
	v_mov_b64_e32 v[98:99], 0
	v_mov_b64_e32 v[100:101], 0
	v_mov_b64_e32 v[102:103], 0
	v_mov_b64_e32 v[104:105], 0
	v_mov_b64_e32 v[106:107], 0
	v_mov_b64_e32 v[108:109], 0
	v_mov_b64_e32 v[110:111], 0
	v_mov_b64_e32 v[112:113], 0
	v_mov_b64_e32 v[114:115], 0
	v_mov_b64_e32 v[116:117], 0
	v_mov_b64_e32 v[118:119], 0
	v_mov_b64_e32 v[120:121], 0
	v_mov_b64_e32 v[122:123], 0
	v_mov_b64_e32 v[124:125], 0
	v_mov_b64_e32 v[126:127], 0
	v_mov_b64_e32 v[128:129], 0
	v_mov_b64_e32 v[130:131], 0
	v_mov_b64_e32 v[132:133], 0
	v_mov_b64_e32 v[134:135], 0
	v_mov_b64_e32 v[136:137], 0
	v_mov_b64_e32 v[138:139], 0
	v_mov_b64_e32 v[140:141], 0
	v_mov_b64_e32 v[142:143], 0

.LBB0_740:
	s_ashr_i32 s11, s10, 31
	v_cmp_lt_i64_e32 vcc, s[14:15], v[164:165]
	s_lshl_b64 s[14:15], s[10:11], 11
	s_add_u32 s14, s41, s14
	s_addc_u32 s15, s54, s15
	s_and_b64 s[18:19], vcc, exec
	s_cselect_b32 s6, s15, s53
	s_cselect_b32 s11, s14, s52
	s_ashr_i32 s13, s12, 31
	s_lshl_b64 s[18:19], s[12:13], 11
	s_add_u32 s18, s55, s18
	s_addc_u32 s19, s56, s19
	s_and_b64 s[60:61], vcc, exec
	s_cselect_b32 s13, s19, s59
	s_cselect_b32 s80, s18, s58
	s_add_u32 s52, s52, 0x40080
	s_addc_u32 s53, s53, 0
	s_add_u32 s81, s58, 0x100
	v_mov_b32_e32 v0, 0
	s_addc_u32 s82, s59, 0
	s_mov_b32 s83, -2
	s_waitcnt lgkmcnt(0)
	v_mov_b32_e32 v1, v0
	v_mov_b32_e32 v2, v0
	v_mov_b32_e32 v3, v0
	v_mov_b32_e32 v4, v0
	v_mov_b32_e32 v5, v0
	v_mov_b32_e32 v6, v0
	v_mov_b32_e32 v7, v0
	v_mov_b32_e32 v16, v0
	v_mov_b32_e32 v17, v0
	v_mov_b32_e32 v18, v0
	v_mov_b32_e32 v19, v0
	v_mov_b32_e32 v20, v0
	v_mov_b32_e32 v21, v0
	v_mov_b32_e32 v22, v0
	v_mov_b32_e32 v23, v0
	v_mov_b32_e32 v32, v0
	v_mov_b32_e32 v33, v0
	v_mov_b32_e32 v34, v0
	v_mov_b32_e32 v35, v0
	s_waitcnt vmcnt(0)
	v_mov_b64_e32 v[8:9], 0
	v_mov_b64_e32 v[10:11], 0
	v_mov_b64_e32 v[12:13], 0
	v_mov_b64_e32 v[14:15], 0
	v_mov_b64_e32 v[24:25], 0
	v_mov_b64_e32 v[26:27], 0
	v_mov_b64_e32 v[28:29], 0
	v_mov_b64_e32 v[30:31], 0
	v_mov_b64_e32 v[36:37], 0
	v_mov_b64_e32 v[38:39], 0
	v_mov_b64_e32 v[40:41], 0
	v_mov_b64_e32 v[42:43], 0
	v_mov_b64_e32 v[44:45], 0
	v_mov_b64_e32 v[46:47], 0
	v_mov_b64_e32 v[48:49], 0
	v_mov_b64_e32 v[50:51], 0
	v_mov_b64_e32 v[52:53], 0
	v_mov_b64_e32 v[54:55], 0
	v_mov_b64_e32 v[56:57], 0
	v_mov_b64_e32 v[58:59], 0
	v_mov_b64_e32 v[60:61], 0
	v_mov_b64_e32 v[62:63], 0
	v_mov_b64_e32 v[64:65], 0
	v_mov_b64_e32 v[66:67], 0
	v_mov_b64_e32 v[68:69], 0
	v_mov_b64_e32 v[70:71], 0
	v_mov_b64_e32 v[72:73], 0
	v_mov_b64_e32 v[74:75], 0
	v_mov_b64_e32 v[76:77], 0
	v_mov_b64_e32 v[78:79], 0
	v_mov_b64_e32 v[80:81], 0
	v_mov_b64_e32 v[82:83], 0
	v_mov_b64_e32 v[84:85], 0
	v_mov_b64_e32 v[86:87], 0
	v_mov_b64_e32 v[88:89], 0
	v_mov_b64_e32 v[90:91], 0
	v_mov_b64_e32 v[92:93], 0
	v_mov_b64_e32 v[94:95], 0
	v_mov_b64_e32 v[96:97], 0
	v_mov_b64_e32 v[98:99], 0
	v_mov_b64_e32 v[100:101], 0
	v_mov_b64_e32 v[102:103], 0
	v_mov_b64_e32 v[104:105], 0
	v_mov_b64_e32 v[106:107], 0
	v_mov_b64_e32 v[108:109], 0
	v_mov_b64_e32 v[110:111], 0
	v_mov_b64_e32 v[112:113], 0
	v_mov_b64_e32 v[114:115], 0
	v_mov_b64_e32 v[116:117], 0
	v_mov_b64_e32 v[118:119], 0
	v_mov_b64_e32 v[120:121], 0
	v_mov_b64_e32 v[122:123], 0
	v_mov_b64_e32 v[124:125], 0
	v_mov_b64_e32 v[126:127], 0

.LBB0_874:
	s_ashr_i32 s61, s60, 31
	s_lshl_b64 s[66:67], s[60:61], 11
	s_add_u32 s66, s34, s66
	s_addc_u32 s67, s35, s67
	s_and_b64 s[68:69], s[62:63], exec
	s_cselect_b32 s3, s67, s85
	s_cselect_b32 s61, s66, s84
	s_ashr_i32 s65, s64, 31
	s_lshl_b64 s[68:69], s[64:65], 11
	s_add_u32 s78, s19, s68
	s_addc_u32 s79, s40, s69
	s_and_b64 s[68:69], s[62:63], exec
	s_cselect_b32 s65, s79, s87
	s_cselect_b32 s73, s78, s86
	s_cmp_lg_u32 s4, 0
	s_cselect_b64 s[82:83], -1, 0
	s_add_u32 s69, s86, 0x100
	s_addc_u32 s71, s87, 0
	s_cmp_eq_u32 s4, 0
	s_cbranch_scc1 .LBB0_878
	s_add_u32 s4, s84, 0x100
	s_addc_u32 s5, s85, 0
	s_add_u32 s86, s86, 0x80080
	v_mov_b32_e32 v0, 0
	s_addc_u32 s87, s87, 0
	s_mov_b32 s68, -2
	v_mov_b32_e32 v1, v0
	v_mov_b32_e32 v2, v0
	v_mov_b32_e32 v3, v0
	v_mov_b32_e32 v4, v0
	v_mov_b32_e32 v5, v0
	v_mov_b32_e32 v6, v0
	v_mov_b32_e32 v7, v0
	v_mov_b32_e32 v8, v0
	v_mov_b32_e32 v9, v0
	v_mov_b32_e32 v10, v0
	v_mov_b32_e32 v11, v0
	v_mov_b32_e32 v12, v0
	v_mov_b32_e32 v13, v0
	v_mov_b32_e32 v14, v0
	v_mov_b32_e32 v15, v0
	v_mov_b32_e32 v16, v0
	v_mov_b32_e32 v17, v0
	v_mov_b32_e32 v18, v0
	v_mov_b32_e32 v19, v0
	v_mov_b32_e32 v20, v0
	v_mov_b32_e32 v21, v0
	v_mov_b32_e32 v22, v0
	v_mov_b32_e32 v23, v0
	v_mov_b32_e32 v24, v0
	v_mov_b32_e32 v25, v0
	v_mov_b32_e32 v26, v0
	v_mov_b32_e32 v27, v0
	v_mov_b32_e32 v28, v0
	v_mov_b32_e32 v29, v0
	v_mov_b32_e32 v30, v0
	v_mov_b32_e32 v31, v0
	v_mov_b32_e32 v32, v0
	v_mov_b32_e32 v33, v0
	v_mov_b32_e32 v34, v0
	v_mov_b32_e32 v35, v0
	s_waitcnt vmcnt(0)
	v_mov_b64_e32 v[36:37], 0
	v_mov_b64_e32 v[38:39], 0
	v_mov_b64_e32 v[40:41], 0
	v_mov_b64_e32 v[42:43], 0
	v_mov_b64_e32 v[44:45], 0
	v_mov_b64_e32 v[46:47], 0
	v_mov_b64_e32 v[48:49], 0
	v_mov_b64_e32 v[50:51], 0
	v_mov_b64_e32 v[52:53], 0
	v_mov_b64_e32 v[54:55], 0
	v_mov_b64_e32 v[56:57], 0
	v_mov_b64_e32 v[58:59], 0
	v_mov_b64_e32 v[60:61], 0
	v_mov_b64_e32 v[62:63], 0
	v_mov_b64_e32 v[64:65], 0
	v_mov_b64_e32 v[66:67], 0
	v_mov_b64_e32 v[68:69], 0
	v_mov_b64_e32 v[70:71], 0
	v_mov_b64_e32 v[72:73], 0
	v_mov_b64_e32 v[74:75], 0
	v_mov_b64_e32 v[76:77], 0
	v_mov_b64_e32 v[78:79], 0
	v_mov_b64_e32 v[80:81], 0
	v_mov_b64_e32 v[82:83], 0
	v_mov_b64_e32 v[84:85], 0
	v_mov_b64_e32 v[86:87], 0
	v_mov_b64_e32 v[88:89], 0
	v_mov_b64_e32 v[90:91], 0
	v_mov_b64_e32 v[92:93], 0
	v_mov_b64_e32 v[94:95], 0

.LBB0_879:
	v_mov_b32_e32 v127, 0
	s_and_b64 vcc, exec, s[86:87]
	v_mov_b32_e32 v126, v127
	v_mov_b32_e32 v125, v127
	v_mov_b32_e32 v124, v127
	v_mov_b32_e32 v123, v127
	v_mov_b32_e32 v122, v127
	v_mov_b32_e32 v121, v127
	v_mov_b32_e32 v120, v127
	v_mov_b32_e32 v119, v127
	v_mov_b32_e32 v118, v127
	v_mov_b32_e32 v117, v127
	v_mov_b32_e32 v116, v127
	v_mov_b32_e32 v115, v127
	v_mov_b32_e32 v114, v127
	v_mov_b32_e32 v113, v127
	v_mov_b32_e32 v112, v127
	v_mov_b32_e32 v111, v127
	v_mov_b32_e32 v110, v127
	v_mov_b32_e32 v109, v127
	v_mov_b32_e32 v108, v127
	v_mov_b32_e32 v107, v127
	v_mov_b32_e32 v106, v127
	v_mov_b32_e32 v105, v127
	v_mov_b32_e32 v104, v127
	v_mov_b32_e32 v103, v127
	v_mov_b32_e32 v102, v127
	v_mov_b32_e32 v101, v127
	v_mov_b32_e32 v100, v127
	v_mov_b32_e32 v99, v127
	v_mov_b32_e32 v98, v127
	v_mov_b32_e32 v97, v127
	v_mov_b32_e32 v96, v127
	s_cbranch_vccz .LBB0_882
	s_cmp_lg_u32 s96, 0
	s_cselect_b64 s[86:87], -1, 0
	s_add_u32 s68, s73, 0x80000
	s_addc_u32 s4, s65, 0
	s_add_u32 s84, s84, 0x40080
	v_mov_b32_e32 v96, 0
	s_addc_u32 s85, s85, 0
	s_mov_b32 s5, -2
	v_mov_b64_e32 v[0:1], 0
	v_mov_b64_e32 v[2:3], 0
	v_mov_b64_e32 v[4:5], 0
	v_mov_b64_e32 v[6:7], 0
	v_mov_b64_e32 v[8:9], 0
	v_mov_b64_e32 v[10:11], 0
	v_mov_b64_e32 v[12:13], 0
	v_mov_b64_e32 v[14:15], 0
	v_mov_b64_e32 v[16:17], 0
	v_mov_b64_e32 v[18:19], 0
	v_mov_b64_e32 v[20:21], 0
	v_mov_b64_e32 v[22:23], 0
	v_mov_b64_e32 v[24:25], 0
	v_mov_b64_e32 v[26:27], 0
	v_mov_b64_e32 v[28:29], 0
	v_mov_b64_e32 v[30:31], 0
	v_mov_b64_e32 v[32:33], 0
	v_mov_b64_e32 v[34:35], 0
	v_mov_b32_e32 v97, 0
	v_mov_b64_e32 v[98:99], 0
	v_mov_b64_e32 v[100:101], 0
	v_mov_b64_e32 v[102:103], 0
	v_mov_b64_e32 v[104:105], 0
	v_mov_b64_e32 v[106:107], 0
	v_mov_b64_e32 v[108:109], 0
	v_mov_b64_e32 v[110:111], 0
	v_mov_b64_e32 v[112:113], 0
	v_mov_b64_e32 v[114:115], 0
	v_mov_b64_e32 v[116:117], 0
	v_mov_b64_e32 v[118:119], 0
	v_mov_b64_e32 v[120:121], 0
	v_mov_b64_e32 v[122:123], 0
	v_mov_b64_e32 v[124:125], 0
	v_mov_b64_e32 v[126:127], 0
	s_waitcnt vmcnt(0)
	v_mov_b64_e32 v[36:37], 0
	v_mov_b64_e32 v[38:39], 0
	v_mov_b64_e32 v[40:41], 0
	v_mov_b64_e32 v[42:43], 0
	v_mov_b64_e32 v[44:45], 0
	v_mov_b64_e32 v[46:47], 0
	v_mov_b64_e32 v[48:49], 0
	v_mov_b64_e32 v[50:51], 0
	v_mov_b64_e32 v[52:53], 0
	v_mov_b64_e32 v[54:55], 0
	v_mov_b64_e32 v[56:57], 0
	v_mov_b64_e32 v[58:59], 0
	v_mov_b64_e32 v[60:61], 0
	v_mov_b64_e32 v[62:63], 0
	v_mov_b64_e32 v[64:65], 0
	v_mov_b64_e32 v[66:67], 0
	v_mov_b64_e32 v[68:69], 0
	v_mov_b64_e32 v[70:71], 0
	v_mov_b64_e32 v[72:73], 0
	v_mov_b64_e32 v[74:75], 0
	v_mov_b64_e32 v[76:77], 0
	v_mov_b64_e32 v[78:79], 0
	v_mov_b64_e32 v[80:81], 0
	v_mov_b64_e32 v[82:83], 0
	v_mov_b64_e32 v[84:85], 0
	v_mov_b64_e32 v[86:87], 0
	v_mov_b64_e32 v[88:89], 0
	v_mov_b64_e32 v[90:91], 0
	v_mov_b64_e32 v[92:93], 0
	v_mov_b64_e32 v[94:95], 0

.LBB0_970:
	s_ashr_i32 s65, s64, 31
	s_lshl_b64 s[78:79], s[64:65], 11
	s_add_u32 s78, s34, s78
	s_addc_u32 s79, s35, s79
	s_and_b64 s[80:81], s[2:3], exec
	s_cselect_b32 s65, s79, s5
	s_cselect_b32 s73, s78, s4
	s_ashr_i32 s67, s66, 31
	s_lshl_b64 s[80:81], s[66:67], 11
	s_add_u32 s80, s40, s80
	s_addc_u32 s81, s41, s81
	s_and_b64 s[82:83], s[2:3], exec
	s_cselect_b32 s67, s81, s7
	s_cselect_b32 s76, s80, s6
	s_add_u32 s4, s4, 0x40080
	s_addc_u32 s5, s5, 0
	s_add_u32 s86, s6, 0x100
	v_mov_b32_e32 v0, 0
	s_addc_u32 s87, s7, 0
	s_mov_b32 s88, -2
	v_mov_b32_e32 v1, 0
	v_mov_b64_e32 v[2:3], 0
	v_mov_b64_e32 v[4:5], 0
	v_mov_b64_e32 v[6:7], 0
	v_mov_b64_e32 v[8:9], 0
	v_mov_b64_e32 v[10:11], 0
	v_mov_b64_e32 v[12:13], 0
	v_mov_b64_e32 v[14:15], 0
	v_mov_b64_e32 v[16:17], 0
	v_mov_b64_e32 v[18:19], 0
	v_mov_b64_e32 v[20:21], 0
	v_mov_b64_e32 v[22:23], 0
	v_mov_b64_e32 v[24:25], 0
	v_mov_b64_e32 v[26:27], 0
	v_mov_b64_e32 v[28:29], 0
	v_mov_b64_e32 v[30:31], 0
	v_mov_b64_e32 v[32:33], 0
	v_mov_b64_e32 v[34:35], 0
	v_mov_b64_e32 v[36:37], 0
	v_mov_b64_e32 v[38:39], 0
	v_mov_b64_e32 v[40:41], 0
	v_mov_b64_e32 v[42:43], 0
	v_mov_b64_e32 v[44:45], 0
	v_mov_b64_e32 v[46:47], 0
	v_mov_b64_e32 v[48:49], 0
	v_mov_b64_e32 v[50:51], 0
	v_mov_b64_e32 v[52:53], 0
	v_mov_b64_e32 v[54:55], 0
	v_mov_b64_e32 v[56:57], 0
	v_mov_b64_e32 v[58:59], 0
	v_mov_b64_e32 v[60:61], 0
	v_mov_b64_e32 v[62:63], 0
	v_mov_b64_e32 v[64:65], 0
	v_mov_b64_e32 v[66:67], 0
	v_mov_b64_e32 v[68:69], 0
	v_mov_b64_e32 v[70:71], 0
	v_mov_b64_e32 v[72:73], 0
	v_mov_b64_e32 v[74:75], 0
	v_mov_b64_e32 v[76:77], 0
	v_mov_b64_e32 v[78:79], 0
	v_mov_b64_e32 v[80:81], 0
	v_mov_b64_e32 v[82:83], 0
	v_mov_b64_e32 v[84:85], 0
	v_mov_b64_e32 v[86:87], 0
	v_mov_b64_e32 v[88:89], 0
	v_mov_b64_e32 v[90:91], 0
	v_mov_b64_e32 v[92:93], 0
	v_mov_b64_e32 v[94:95], 0
	v_mov_b64_e32 v[96:97], 0
	v_mov_b64_e32 v[98:99], 0
	v_mov_b64_e32 v[100:101], 0
	v_mov_b64_e32 v[102:103], 0
	v_mov_b64_e32 v[104:105], 0
	v_mov_b64_e32 v[106:107], 0
	v_mov_b64_e32 v[108:109], 0
	v_mov_b64_e32 v[110:111], 0
	v_mov_b64_e32 v[112:113], 0
	v_mov_b64_e32 v[114:115], 0
	v_mov_b64_e32 v[116:117], 0
	v_mov_b64_e32 v[118:119], 0
	v_mov_b64_e32 v[124:125], 0
	v_mov_b64_e32 v[126:127], 0
	v_mov_b64_e32 v[132:133], 0
	v_mov_b64_e32 v[134:135], 0

.LBB0_1079:
	s_add_u32 s73, s38, 0x100
	v_mov_b32_e32 v0, 0
	s_addc_u32 s76, s39, 0
	s_mov_b32 s77, -2
	s_waitcnt lgkmcnt(0)
	v_mov_b32_e32 v1, 0
	v_mov_b64_e32 v[2:3], 0
	v_mov_b64_e32 v[4:5], 0
	v_mov_b64_e32 v[6:7], 0
	v_mov_b64_e32 v[8:9], 0
	v_mov_b64_e32 v[10:11], 0
	v_mov_b64_e32 v[12:13], 0
	v_mov_b64_e32 v[14:15], 0
	v_mov_b64_e32 v[16:17], 0
	v_mov_b64_e32 v[18:19], 0
	v_mov_b64_e32 v[20:21], 0
	v_mov_b64_e32 v[22:23], 0
	v_mov_b64_e32 v[24:25], 0
	v_mov_b64_e32 v[26:27], 0
	v_mov_b64_e32 v[28:29], 0
	v_mov_b64_e32 v[30:31], 0
	v_mov_b64_e32 v[32:33], 0
	v_mov_b64_e32 v[34:35], 0
	v_mov_b64_e32 v[36:37], 0
	v_mov_b64_e32 v[38:39], 0
	v_mov_b64_e32 v[40:41], 0
	v_mov_b64_e32 v[42:43], 0
	v_mov_b64_e32 v[44:45], 0
	v_mov_b64_e32 v[46:47], 0
	v_mov_b64_e32 v[48:49], 0
	v_mov_b64_e32 v[50:51], 0
	v_mov_b64_e32 v[52:53], 0
	v_mov_b64_e32 v[54:55], 0
	v_mov_b64_e32 v[56:57], 0
	v_mov_b64_e32 v[58:59], 0
	v_mov_b64_e32 v[60:61], 0
	v_mov_b64_e32 v[62:63], 0
	v_mov_b64_e32 v[64:65], 0
	v_mov_b64_e32 v[66:67], 0
	v_mov_b64_e32 v[68:69], 0
	v_mov_b64_e32 v[70:71], 0
	v_mov_b64_e32 v[72:73], 0
	v_mov_b64_e32 v[74:75], 0
	v_mov_b64_e32 v[76:77], 0
	v_mov_b64_e32 v[78:79], 0
	v_mov_b64_e32 v[80:81], 0
	v_mov_b64_e32 v[82:83], 0
	v_mov_b64_e32 v[84:85], 0
	v_mov_b64_e32 v[86:87], 0
	v_mov_b64_e32 v[88:89], 0
	v_mov_b64_e32 v[90:91], 0
	v_mov_b64_e32 v[92:93], 0
	v_mov_b64_e32 v[94:95], 0
	v_mov_b64_e32 v[96:97], 0
	v_mov_b64_e32 v[98:99], 0
	v_mov_b64_e32 v[100:101], 0
	v_mov_b64_e32 v[102:103], 0
	v_mov_b64_e32 v[104:105], 0
	v_mov_b64_e32 v[106:107], 0
	v_mov_b64_e32 v[108:109], 0
	v_mov_b64_e32 v[110:111], 0
	v_mov_b64_e32 v[112:113], 0
	v_mov_b64_e32 v[114:115], 0
	v_mov_b64_e32 v[116:117], 0
	v_mov_b64_e32 v[118:119], 0
	v_mov_b64_e32 v[120:121], 0
	v_mov_b64_e32 v[122:123], 0
	v_mov_b64_e32 v[124:125], 0
	v_mov_b64_e32 v[126:127], 0

.LBB0_1180:
	s_ashr_i32 s37, s36, 31
	s_lshl_b64 s[44:45], s[36:37], 11
	s_add_u32 s44, s34, s44
	s_addc_u32 s45, s35, s45
	s_and_b64 s[52:53], s[0:1], exec
	s_cselect_b32 s37, s45, s3
	s_cselect_b32 s52, s44, s2
	s_ashr_i32 s39, s38, 31
	s_lshl_b64 s[54:55], s[38:39], 11
	s_add_u32 s60, s67, s54
	s_addc_u32 s61, s78, s55
	s_and_b64 s[54:55], s[0:1], exec
	s_cselect_b32 s39, s61, s63
	s_cselect_b32 s53, s60, s62
	s_add_u32 s2, s2, 0x40080
	s_addc_u32 s3, s3, 0
	s_add_u32 s54, s62, 0x100
	v_mov_b32_e32 v0, 0
	s_addc_u32 s55, s63, 0
	s_mov_b32 s56, -2
	v_mov_b32_e32 v1, 0
	v_mov_b64_e32 v[2:3], 0
	v_mov_b64_e32 v[4:5], 0
	v_mov_b64_e32 v[6:7], 0
	v_mov_b64_e32 v[8:9], 0
	v_mov_b64_e32 v[10:11], 0
	v_mov_b64_e32 v[12:13], 0
	v_mov_b64_e32 v[14:15], 0
	v_mov_b64_e32 v[16:17], 0
	v_mov_b64_e32 v[18:19], 0
	v_mov_b64_e32 v[20:21], 0
	v_mov_b64_e32 v[22:23], 0
	v_mov_b64_e32 v[24:25], 0
	v_mov_b64_e32 v[26:27], 0
	v_mov_b64_e32 v[28:29], 0
	v_mov_b64_e32 v[30:31], 0
	v_mov_b64_e32 v[32:33], 0
	v_mov_b64_e32 v[34:35], 0
	v_mov_b64_e32 v[36:37], 0
	v_mov_b64_e32 v[38:39], 0
	v_mov_b64_e32 v[40:41], 0
	v_mov_b64_e32 v[42:43], 0
	v_mov_b64_e32 v[44:45], 0
	v_mov_b64_e32 v[46:47], 0
	v_mov_b64_e32 v[48:49], 0
	v_mov_b64_e32 v[50:51], 0
	v_mov_b64_e32 v[52:53], 0
	v_mov_b64_e32 v[54:55], 0
	v_mov_b64_e32 v[56:57], 0
	v_mov_b64_e32 v[58:59], 0
	v_mov_b64_e32 v[60:61], 0
	v_mov_b64_e32 v[62:63], 0
	v_mov_b64_e32 v[64:65], 0
	v_mov_b64_e32 v[66:67], 0
	v_mov_b64_e32 v[68:69], 0
	v_mov_b64_e32 v[70:71], 0
	v_mov_b64_e32 v[72:73], 0
	v_mov_b64_e32 v[74:75], 0
	v_mov_b64_e32 v[76:77], 0
	v_mov_b64_e32 v[78:79], 0
	v_mov_b64_e32 v[80:81], 0
	v_mov_b64_e32 v[82:83], 0
	v_mov_b64_e32 v[84:85], 0
	v_mov_b64_e32 v[86:87], 0
	v_mov_b64_e32 v[88:89], 0
	v_mov_b64_e32 v[90:91], 0
	v_mov_b64_e32 v[92:93], 0
	v_mov_b64_e32 v[94:95], 0
	v_mov_b64_e32 v[96:97], 0
	v_mov_b64_e32 v[98:99], 0
	v_mov_b64_e32 v[100:101], 0
	v_mov_b64_e32 v[102:103], 0
	v_mov_b64_e32 v[104:105], 0
	v_mov_b64_e32 v[106:107], 0
	v_mov_b64_e32 v[108:109], 0
	v_mov_b64_e32 v[110:111], 0
	v_mov_b64_e32 v[112:113], 0
	v_mov_b64_e32 v[114:115], 0
	v_mov_b64_e32 v[116:117], 0
	v_mov_b64_e32 v[118:119], 0
	v_mov_b64_e32 v[120:121], 0
	v_mov_b64_e32 v[122:123], 0
	v_mov_b64_e32 v[124:125], 0
	v_mov_b64_e32 v[126:127], 0

.LBB0_1529:
	s_ashr_i32 s11, s10, 31
	v_cmp_lt_i64_e32 vcc, s[14:15], v[164:165]
	s_lshl_b64 s[14:15], s[10:11], 11
	s_add_u32 s14, s41, s14
	s_addc_u32 s15, s42, s15
	s_and_b64 s[18:19], vcc, exec
	s_cselect_b32 s11, s15, s25
	s_cselect_b32 s61, s14, s24
	s_ashr_i32 s13, s12, 31
	s_lshl_b64 s[18:19], s[12:13], 11
	s_add_u32 s18, s43, s18
	s_addc_u32 s19, s44, s19
	s_and_b64 s[38:39], vcc, exec
	s_cselect_b32 s13, s19, s37
	s_cselect_b32 s62, s18, s36
	s_add_u32 s24, s24, 0x40080
	s_addc_u32 s25, s25, 0
	s_add_u32 s63, s36, 0x100
	v_mov_b32_e32 v0, 0
	s_addc_u32 s64, s37, 0
	s_mov_b32 s65, -2
	s_waitcnt lgkmcnt(0)
	v_mov_b32_e32 v1, v0
	v_mov_b32_e32 v2, v0
	v_mov_b32_e32 v3, v0
	v_mov_b32_e32 v4, v0
	v_mov_b32_e32 v5, v0
	v_mov_b32_e32 v6, v0
	v_mov_b32_e32 v7, v0
	v_mov_b32_e32 v16, v0
	v_mov_b32_e32 v17, v0
	v_mov_b32_e32 v18, v0
	v_mov_b32_e32 v19, v0
	v_mov_b32_e32 v20, v0
	v_mov_b32_e32 v21, v0
	v_mov_b32_e32 v22, v0
	v_mov_b32_e32 v23, v0
	v_mov_b32_e32 v32, v0
	v_mov_b32_e32 v33, v0
	v_mov_b32_e32 v34, v0
	v_mov_b32_e32 v35, v0
	s_waitcnt vmcnt(0)
	v_mov_b64_e32 v[8:9], 0
	v_mov_b64_e32 v[10:11], 0
	v_mov_b64_e32 v[12:13], 0
	v_mov_b64_e32 v[14:15], 0
	v_mov_b64_e32 v[24:25], 0
	v_mov_b64_e32 v[26:27], 0
	v_mov_b64_e32 v[28:29], 0
	v_mov_b64_e32 v[30:31], 0
	v_mov_b64_e32 v[36:37], 0
	v_mov_b64_e32 v[38:39], 0
	v_mov_b64_e32 v[40:41], 0
	v_mov_b64_e32 v[42:43], 0
	v_mov_b64_e32 v[44:45], 0
	v_mov_b64_e32 v[46:47], 0
	v_mov_b64_e32 v[48:49], 0
	v_mov_b64_e32 v[50:51], 0
	v_mov_b64_e32 v[52:53], 0
	v_mov_b64_e32 v[54:55], 0
	v_mov_b64_e32 v[56:57], 0
	v_mov_b64_e32 v[58:59], 0
	v_mov_b64_e32 v[60:61], 0
	v_mov_b64_e32 v[62:63], 0
	v_mov_b64_e32 v[64:65], 0
	v_mov_b64_e32 v[66:67], 0
	v_mov_b64_e32 v[68:69], 0
	v_mov_b64_e32 v[70:71], 0
	v_mov_b64_e32 v[72:73], 0
	v_mov_b64_e32 v[74:75], 0
	v_mov_b64_e32 v[76:77], 0
	v_mov_b64_e32 v[78:79], 0
	v_mov_b64_e32 v[80:81], 0
	v_mov_b64_e32 v[82:83], 0
	v_mov_b64_e32 v[84:85], 0
	v_mov_b64_e32 v[86:87], 0
	v_mov_b64_e32 v[88:89], 0
	v_mov_b64_e32 v[90:91], 0
	v_mov_b64_e32 v[92:93], 0
	v_mov_b64_e32 v[94:95], 0
	v_mov_b64_e32 v[96:97], 0
	v_mov_b64_e32 v[98:99], 0
	v_mov_b64_e32 v[100:101], 0
	v_mov_b64_e32 v[102:103], 0
	v_mov_b64_e32 v[104:105], 0
	v_mov_b64_e32 v[106:107], 0
	v_mov_b64_e32 v[108:109], 0
	v_mov_b64_e32 v[110:111], 0
	v_mov_b64_e32 v[112:113], 0
	v_mov_b64_e32 v[114:115], 0
	v_mov_b64_e32 v[116:117], 0
	v_mov_b64_e32 v[118:119], 0
	v_mov_b64_e32 v[120:121], 0
	v_mov_b64_e32 v[122:123], 0
	v_mov_b64_e32 v[124:125], 0
	v_mov_b64_e32 v[126:127], 0

.LBB0_1656:
	s_ashr_i32 s39, s38, 31
	s_lshl_b64 s[6:7], s[38:39], 11
	s_add_u32 s44, s34, s6
	s_addc_u32 s45, s35, s7
	s_and_b64 s[6:7], s[40:41], exec
	s_cselect_b32 s3, s45, s49
	s_cselect_b32 s5, s44, s48
	s_ashr_i32 s43, s42, 31
	s_lshl_b64 s[6:7], s[42:43], 11
	s_add_u32 s46, s37, s6
	s_addc_u32 s47, s52, s7
	s_and_b64 s[6:7], s[40:41], exec
	s_cselect_b32 s39, s47, s51
	s_cselect_b32 s43, s46, s50
	s_cmp_lg_u32 s54, 0
	s_cselect_b64 s[6:7], -1, 0
	s_add_u32 s85, s50, 0x100
	s_addc_u32 s86, s51, 0
	s_cmp_eq_u32 s54, 0
	s_cbranch_scc1 .LBB0_1660
	s_add_u32 s56, s48, 0x100
	s_addc_u32 s57, s49, 0
	s_add_u32 s50, s50, 0x80080
	v_mov_b32_e32 v0, 0
	s_addc_u32 s51, s51, 0
	s_mov_b32 s58, -2
	v_mov_b32_e32 v1, 0
	v_mov_b64_e32 v[2:3], 0
	v_mov_b64_e32 v[4:5], 0
	v_mov_b64_e32 v[6:7], 0
	v_mov_b64_e32 v[8:9], 0
	v_mov_b64_e32 v[10:11], 0
	v_mov_b64_e32 v[12:13], 0
	v_mov_b64_e32 v[14:15], 0
	v_mov_b64_e32 v[16:17], 0
	v_mov_b64_e32 v[18:19], 0
	v_mov_b64_e32 v[20:21], 0
	v_mov_b64_e32 v[22:23], 0
	v_mov_b64_e32 v[24:25], 0
	v_mov_b64_e32 v[26:27], 0
	v_mov_b64_e32 v[28:29], 0
	v_mov_b64_e32 v[30:31], 0
	v_mov_b64_e32 v[32:33], 0
	v_mov_b64_e32 v[34:35], 0
	v_mov_b64_e32 v[36:37], 0
	v_mov_b64_e32 v[38:39], 0
	v_mov_b64_e32 v[40:41], 0
	v_mov_b64_e32 v[42:43], 0
	v_mov_b64_e32 v[44:45], 0
	v_mov_b64_e32 v[46:47], 0
	v_mov_b64_e32 v[48:49], 0
	v_mov_b64_e32 v[50:51], 0
	v_mov_b64_e32 v[52:53], 0
	v_mov_b64_e32 v[54:55], 0
	v_mov_b64_e32 v[56:57], 0
	v_mov_b64_e32 v[58:59], 0
	v_mov_b64_e32 v[60:61], 0
	v_mov_b64_e32 v[62:63], 0
	v_mov_b64_e32 v[64:65], 0
	v_mov_b64_e32 v[66:67], 0
	v_mov_b64_e32 v[68:69], 0
	v_mov_b64_e32 v[70:71], 0
	v_mov_b64_e32 v[72:73], 0
	v_mov_b64_e32 v[74:75], 0
	v_mov_b64_e32 v[76:77], 0
	v_mov_b64_e32 v[78:79], 0
	v_mov_b64_e32 v[80:81], 0
	v_mov_b64_e32 v[82:83], 0
	v_mov_b64_e32 v[84:85], 0
	v_mov_b64_e32 v[86:87], 0
	v_mov_b64_e32 v[88:89], 0
	v_mov_b64_e32 v[90:91], 0
	v_mov_b64_e32 v[92:93], 0
	v_mov_b64_e32 v[94:95], 0

.LBB0_1661:
	v_mov_b32_e32 v127, 0
	s_and_b64 vcc, exec, s[50:51]
	v_mov_b32_e32 v126, v127
	v_mov_b32_e32 v125, v127
	v_mov_b32_e32 v124, v127
	v_mov_b32_e32 v123, v127
	v_mov_b32_e32 v122, v127
	v_mov_b32_e32 v121, v127
	v_mov_b32_e32 v120, v127
	v_mov_b32_e32 v119, v127
	v_mov_b32_e32 v118, v127
	v_mov_b32_e32 v117, v127
	v_mov_b32_e32 v116, v127
	v_mov_b32_e32 v115, v127
	v_mov_b32_e32 v114, v127
	v_mov_b32_e32 v113, v127
	v_mov_b32_e32 v112, v127
	v_mov_b32_e32 v111, v127
	v_mov_b32_e32 v110, v127
	v_mov_b32_e32 v109, v127
	v_mov_b32_e32 v108, v127
	v_mov_b32_e32 v107, v127
	v_mov_b32_e32 v106, v127
	v_mov_b32_e32 v105, v127
	v_mov_b32_e32 v104, v127
	v_mov_b32_e32 v103, v127
	v_mov_b32_e32 v102, v127
	v_mov_b32_e32 v101, v127
	v_mov_b32_e32 v100, v127
	v_mov_b32_e32 v99, v127
	v_mov_b32_e32 v98, v127
	v_mov_b32_e32 v97, v127
	v_mov_b32_e32 v96, v127
	s_cbranch_vccz .LBB0_1664
	s_cmp_lg_u32 s81, 0
	s_cselect_b64 s[50:51], -1, 0
	s_add_u32 s87, s43, 0x80000
	s_addc_u32 s88, s39, 0
	s_add_u32 s48, s48, 0x40080
	v_mov_b32_e32 v96, 0
	s_addc_u32 s49, s49, 0
	s_mov_b32 s89, -2
	v_mov_b64_e32 v[0:1], 0
	v_mov_b64_e32 v[2:3], 0
	v_mov_b64_e32 v[4:5], 0
	v_mov_b64_e32 v[6:7], 0
	v_mov_b64_e32 v[8:9], 0
	v_mov_b64_e32 v[10:11], 0
	v_mov_b64_e32 v[12:13], 0
	v_mov_b64_e32 v[14:15], 0
	v_mov_b64_e32 v[16:17], 0
	v_mov_b64_e32 v[18:19], 0
	v_mov_b64_e32 v[20:21], 0
	v_mov_b64_e32 v[22:23], 0
	v_mov_b64_e32 v[24:25], 0
	v_mov_b64_e32 v[26:27], 0
	v_mov_b64_e32 v[28:29], 0
	v_mov_b64_e32 v[30:31], 0
	v_mov_b64_e32 v[32:33], 0
	v_mov_b64_e32 v[34:35], 0
	v_mov_b64_e32 v[36:37], 0
	v_mov_b64_e32 v[38:39], 0
	v_mov_b64_e32 v[40:41], 0
	v_mov_b64_e32 v[42:43], 0
	v_mov_b64_e32 v[44:45], 0
	v_mov_b64_e32 v[46:47], 0
	v_mov_b64_e32 v[48:49], 0
	v_mov_b64_e32 v[50:51], 0
	v_mov_b64_e32 v[52:53], 0
	v_mov_b64_e32 v[54:55], 0
	v_mov_b64_e32 v[56:57], 0
	v_mov_b64_e32 v[58:59], 0
	v_mov_b64_e32 v[60:61], 0
	v_mov_b64_e32 v[62:63], 0
	v_mov_b64_e32 v[64:65], 0
	v_mov_b64_e32 v[66:67], 0
	v_mov_b64_e32 v[68:69], 0
	v_mov_b64_e32 v[70:71], 0
	v_mov_b64_e32 v[72:73], 0
	v_mov_b64_e32 v[74:75], 0
	v_mov_b64_e32 v[76:77], 0
	v_mov_b64_e32 v[78:79], 0
	v_mov_b64_e32 v[80:81], 0
	v_mov_b64_e32 v[82:83], 0
	v_mov_b64_e32 v[84:85], 0
	v_mov_b64_e32 v[86:87], 0
	v_mov_b64_e32 v[88:89], 0
	v_mov_b64_e32 v[90:91], 0
	v_mov_b64_e32 v[92:93], 0
	v_mov_b64_e32 v[94:95], 0
	v_mov_b32_e32 v97, 0
	v_mov_b64_e32 v[98:99], 0
	v_mov_b64_e32 v[100:101], 0
	v_mov_b64_e32 v[102:103], 0
	v_mov_b64_e32 v[104:105], 0
	v_mov_b64_e32 v[106:107], 0
	v_mov_b64_e32 v[108:109], 0
	v_mov_b64_e32 v[110:111], 0
	v_mov_b64_e32 v[112:113], 0
	v_mov_b64_e32 v[114:115], 0
	v_mov_b64_e32 v[116:117], 0
	v_mov_b64_e32 v[118:119], 0
	v_mov_b64_e32 v[120:121], 0
	v_mov_b64_e32 v[122:123], 0
	v_mov_b64_e32 v[124:125], 0
	v_mov_b64_e32 v[126:127], 0

.LBB0_1747:
	s_ashr_i32 s49, s48, 31
	s_lshl_b64 s[6:7], s[48:49], 11
	s_add_u32 s56, s34, s6
	s_addc_u32 s57, s35, s7
	s_and_b64 s[6:7], s[50:51], exec
	s_cselect_b32 s3, s57, s9
	s_cselect_b32 s5, s56, s8
	s_ashr_i32 s55, s54, 31
	s_lshl_b64 s[6:7], s[54:55], 11
	s_add_u32 s58, s45, s6
	s_addc_u32 s59, s47, s7
	s_and_b64 s[6:7], s[50:51], exec
	s_cselect_b32 s49, s59, s61
	s_cselect_b32 s52, s58, s60
	s_cmp_lg_u32 s62, 0
	s_cselect_b64 s[6:7], -1, 0
	s_add_u32 s53, s60, 0x100
	s_addc_u32 s55, s61, 0
	s_cmp_eq_u32 s62, 0
	s_cbranch_scc1 .LBB0_1800
	s_add_u32 s64, s8, 0x100
	s_addc_u32 s65, s9, 0
	s_add_u32 s60, s60, 0x80080
	v_mov_b32_e32 v14, 0
	s_addc_u32 s61, s61, 0
	s_mov_b32 s66, -2
	v_mov_b32_e32 v15, v14
	v_mov_b32_e32 v16, v14
	v_mov_b32_e32 v17, v14
	v_mov_b32_e32 v22, v14
	v_mov_b32_e32 v23, v14
	v_mov_b32_e32 v24, v14
	v_mov_b32_e32 v25, v14
	v_mov_b32_e32 v34, v14
	v_mov_b32_e32 v35, v14
	s_waitcnt vmcnt(0)
	v_mov_b64_e32 v[36:37], 0
	v_mov_b64_e32 v[42:43], 0
	v_mov_b64_e32 v[44:45], 0
	v_mov_b64_e32 v[50:51], 0
	v_mov_b64_e32 v[52:53], 0
	v_mov_b64_e32 v[54:55], 0
	v_mov_b64_e32 v[56:57], 0
	v_mov_b64_e32 v[58:59], 0
	v_mov_b64_e32 v[60:61], 0
	v_mov_b64_e32 v[62:63], 0
	v_mov_b64_e32 v[64:65], 0
	v_mov_b64_e32 v[66:67], 0
	v_mov_b64_e32 v[68:69], 0
	v_mov_b64_e32 v[70:71], 0
	v_mov_b64_e32 v[72:73], 0
	v_mov_b64_e32 v[74:75], 0
	v_mov_b64_e32 v[76:77], 0
	v_mov_b64_e32 v[78:79], 0
	v_mov_b64_e32 v[80:81], 0
	v_mov_b64_e32 v[82:83], 0
	v_mov_b64_e32 v[84:85], 0
	v_mov_b64_e32 v[86:87], 0
	v_mov_b64_e32 v[88:89], 0
	v_mov_b64_e32 v[90:91], 0
	v_mov_b64_e32 v[92:93], 0
	v_mov_b64_e32 v[94:95], 0
	v_mov_b64_e32 v[96:97], 0
	v_mov_b64_e32 v[98:99], 0
	v_mov_b64_e32 v[100:101], 0
	v_mov_b64_e32 v[102:103], 0
	v_mov_b64_e32 v[104:105], 0
	v_mov_b64_e32 v[106:107], 0
	v_mov_b64_e32 v[108:109], 0
	v_mov_b64_e32 v[110:111], 0
	v_mov_b64_e32 v[112:113], 0
	v_mov_b64_e32 v[114:115], 0
	v_mov_b64_e32 v[116:117], 0
	v_mov_b64_e32 v[118:119], 0
	v_mov_b64_e32 v[120:121], 0
	v_mov_b64_e32 v[122:123], 0
	v_mov_b64_e32 v[124:125], 0
	v_mov_b64_e32 v[126:127], 0
	v_mov_b64_e32 v[128:129], 0

.LBB0_1751:
	s_cmp_lg_u32 s92, 0
	s_cselect_b64 s[60:61], -1, 0
	s_add_u32 s68, s52, 0x80000
	s_addc_u32 s69, s49, 0
	s_add_u32 s8, s8, 0x40080
	v_mov_b32_e32 v2, 0
	s_addc_u32 s9, s9, 0
	s_mov_b32 s72, -2
	v_mov_b32_e32 v3, v2
	v_mov_b32_e32 v4, v2
	v_mov_b32_e32 v5, v2
	v_mov_b32_e32 v6, v2
	v_mov_b32_e32 v7, v2
	v_mov_b32_e32 v8, v2
	v_mov_b32_e32 v9, v2
	v_mov_b32_e32 v10, v2
	v_mov_b32_e32 v11, v2
	v_mov_b32_e32 v12, v2
	v_mov_b32_e32 v13, v2
	v_mov_b32_e32 v18, v2
	v_mov_b32_e32 v19, v2
	v_mov_b32_e32 v20, v2
	v_mov_b32_e32 v21, v2
	v_mov_b32_e32 v26, v2
	v_mov_b32_e32 v27, v2
	v_mov_b32_e32 v28, v2
	v_mov_b32_e32 v29, v2
	v_mov_b32_e32 v30, v2
	v_mov_b32_e32 v31, v2
	v_mov_b32_e32 v32, v2
	v_mov_b32_e32 v33, v2
	s_waitcnt vmcnt(0)
	v_mov_b64_e32 v[14:15], 0
	v_mov_b64_e32 v[16:17], 0
	v_mov_b64_e32 v[22:23], 0
	v_mov_b64_e32 v[24:25], 0
	v_mov_b64_e32 v[34:35], 0
	v_mov_b64_e32 v[36:37], 0
	v_mov_b64_e32 v[38:39], 0
	v_mov_b64_e32 v[40:41], 0
	v_mov_b64_e32 v[42:43], 0
	v_mov_b64_e32 v[44:45], 0
	v_mov_b64_e32 v[46:47], 0
	v_mov_b64_e32 v[48:49], 0
	v_mov_b64_e32 v[50:51], 0
	v_mov_b64_e32 v[52:53], 0
	v_mov_b64_e32 v[54:55], 0
	v_mov_b64_e32 v[56:57], 0
	v_mov_b64_e32 v[58:59], 0
	v_mov_b64_e32 v[60:61], 0
	v_mov_b64_e32 v[62:63], 0
	v_mov_b64_e32 v[64:65], 0
	v_mov_b64_e32 v[66:67], 0
	v_mov_b64_e32 v[68:69], 0
	v_mov_b64_e32 v[70:71], 0
	v_mov_b64_e32 v[72:73], 0
	v_mov_b64_e32 v[74:75], 0
	v_mov_b64_e32 v[76:77], 0
	v_mov_b64_e32 v[78:79], 0
	v_mov_b64_e32 v[80:81], 0
	v_mov_b64_e32 v[82:83], 0
	v_mov_b64_e32 v[84:85], 0
	v_mov_b64_e32 v[86:87], 0
	v_mov_b64_e32 v[88:89], 0
	v_mov_b64_e32 v[90:91], 0
	v_mov_b64_e32 v[92:93], 0
	v_mov_b64_e32 v[94:95], 0
	v_mov_b64_e32 v[96:97], 0
	v_mov_b64_e32 v[98:99], 0
	v_mov_b64_e32 v[100:101], 0
	v_mov_b64_e32 v[102:103], 0
	v_mov_b64_e32 v[104:105], 0
	v_mov_b64_e32 v[106:107], 0
	v_mov_b64_e32 v[108:109], 0
	v_mov_b64_e32 v[110:111], 0
	v_mov_b64_e32 v[112:113], 0
	v_mov_b64_e32 v[114:115], 0
	v_mov_b64_e32 v[116:117], 0
	v_mov_b64_e32 v[118:119], 0
	v_mov_b64_e32 v[120:121], 0
	v_mov_b64_e32 v[122:123], 0
	v_mov_b64_e32 v[124:125], 0
	v_mov_b64_e32 v[126:127], 0
	v_mov_b64_e32 v[128:129], 0

.LBB0_1881:
	s_add_u32 s56, s24, 0x100
	v_mov_b32_e32 v0, 0
	s_addc_u32 s57, s25, 0
	s_mov_b32 s58, -2
	v_mov_b32_e32 v1, v0
	v_mov_b32_e32 v2, v0
	v_mov_b32_e32 v3, v0
	v_mov_b32_e32 v4, v0
	v_mov_b32_e32 v5, v0
	v_mov_b32_e32 v6, v0
	v_mov_b32_e32 v7, v0
	v_mov_b32_e32 v16, v0
	v_mov_b32_e32 v17, v0
	v_mov_b32_e32 v18, v0
	v_mov_b32_e32 v19, v0
	v_mov_b32_e32 v20, v0
	v_mov_b32_e32 v21, v0
	v_mov_b32_e32 v22, v0
	v_mov_b32_e32 v23, v0
	v_mov_b32_e32 v32, v0
	v_mov_b32_e32 v33, v0
	v_mov_b32_e32 v34, v0
	v_mov_b32_e32 v35, v0
	s_waitcnt vmcnt(0)
	v_mov_b64_e32 v[8:9], 0
	v_mov_b64_e32 v[10:11], 0
	v_mov_b64_e32 v[12:13], 0
	v_mov_b64_e32 v[14:15], 0
	v_mov_b64_e32 v[24:25], 0
	v_mov_b64_e32 v[26:27], 0
	v_mov_b64_e32 v[28:29], 0
	v_mov_b64_e32 v[30:31], 0
	v_mov_b64_e32 v[36:37], 0
	v_mov_b64_e32 v[38:39], 0
	v_mov_b64_e32 v[40:41], 0
	v_mov_b64_e32 v[42:43], 0
	v_mov_b64_e32 v[44:45], 0
	v_mov_b64_e32 v[46:47], 0
	v_mov_b64_e32 v[48:49], 0
	v_mov_b64_e32 v[50:51], 0
	v_mov_b64_e32 v[52:53], 0
	v_mov_b64_e32 v[54:55], 0
	v_mov_b64_e32 v[56:57], 0
	v_mov_b64_e32 v[58:59], 0
	v_mov_b64_e32 v[60:61], 0
	v_mov_b64_e32 v[62:63], 0
	v_mov_b64_e32 v[64:65], 0
	v_mov_b64_e32 v[66:67], 0
	v_mov_b64_e32 v[68:69], 0
	v_mov_b64_e32 v[70:71], 0
	v_mov_b64_e32 v[72:73], 0
	v_mov_b64_e32 v[74:75], 0
	v_mov_b64_e32 v[76:77], 0
	v_mov_b64_e32 v[78:79], 0
	v_mov_b64_e32 v[80:81], 0
	v_mov_b64_e32 v[82:83], 0
	v_mov_b64_e32 v[84:85], 0
	v_mov_b64_e32 v[86:87], 0
	v_mov_b64_e32 v[88:89], 0
	v_mov_b64_e32 v[90:91], 0
	v_mov_b64_e32 v[92:93], 0
	v_mov_b64_e32 v[94:95], 0
	v_mov_b64_e32 v[96:97], 0
	v_mov_b64_e32 v[98:99], 0
	v_mov_b64_e32 v[100:101], 0
	v_mov_b64_e32 v[102:103], 0
	v_mov_b64_e32 v[104:105], 0
	v_mov_b64_e32 v[106:107], 0
	v_mov_b64_e32 v[108:109], 0
	v_mov_b64_e32 v[110:111], 0
	v_mov_b64_e32 v[112:113], 0
	v_mov_b64_e32 v[114:115], 0
	v_mov_b64_e32 v[116:117], 0
	v_mov_b64_e32 v[118:119], 0
	v_mov_b64_e32 v[120:121], 0
	v_mov_b64_e32 v[122:123], 0
	v_mov_b64_e32 v[124:125], 0
	v_mov_b64_e32 v[126:127], 0
